# static priority, other half: flips removed from the GEMM K-loops, one s_setprio 1 for waves 0-3 at kernel start
# speedup vs baseline: 1.0055x; 1.0051x over previous
_Z3fwd4Args:
	s_mov_b32 s60, s2
	s_load_dwordx8 s[20:27], s[0:1], 0x80
	s_load_dword s2, s[0:1], 0xa8
	v_cmp_gt_u32_e32 vcc, 64, v0
	s_waitcnt lgkmcnt(0)
	v_writelane_b32 v252, s2, 0
	s_add_u32 s2, s0, 0xa8
	s_addc_u32 s3, s1, 0
	v_writelane_b32 v252, s2, 1
	s_nop 1
	v_writelane_b32 v252, s3, 2
	s_and_saveexec_b64 s[2:3], vcc
	v_lshl_add_u32 v1, v0, 2, 0
	v_add_u32_e32 v1, 0x24000, v1
	v_mov_b32_e32 v2, 0
	ds_write_b32 v1, v2
	s_or_b64 exec, exec, s[2:3]
	s_load_dwordx2 s[2:3], s[0:1], 0xa0
	s_waitcnt lgkmcnt(0)
	s_barrier
	v_readfirstlane_b32 s4, v0
	s_nop 3
	s_lshr_b32 s4, s4, 6
	s_cmp_lt_u32 s4, 4
	s_cbranch_scc0 .Lprio_done
	s_setprio 1
